# e6 (groupnorm/gate elementwise) row loop: next row's loads prefetched during the current row's compute
# baseline (speedup 1.0000x reference)
; __device__ __forceinline__ void unpack8(const u32x4 w, float (&f)[8]) { f[0] = bflo(w.x); f[1] = bfhi(w.x); f[2] = bflo(w.y); f[3] = bfhi(w.y); f[4] = bflo(w.z); f[5] = bfhi(w.z); f[6] = bflo(w.w); f[7] = bfhi(w.w); }
; __device__ __forceinline__ void e6_phase(const bf16* LO, const float* COEF, const bf16* SV, const float* ln_w, const float* ln_b, bf16* mix, int gw, int ngw, int lane) {
;     const int hf = gw & 1, c = hf * 512 + lane * 8, h = c >> 6, cl = (lane & 7) * 8;
;     float lw[8], lb[8]; ld8f(ln_w + c, lw); ld8f(ln_b + c, lb);
;     for (int m = gw >> 1; m < T; m += ngw >> 1) { const int t = m & (SEQ - 1), b = m >> 12;
;         bf16* yp = mix + (size_t)m * D + 1024 + c;
;         const size_t idx = (size_t)(b * 16 + h) * SEQ + t;
;         float y[8], v[8], g[8];
;         unpack8(*(const u32x4*)yp, y); unpack8(*(const u32x4*)(SV + idx * 64 + cl), v); unpack8(*(const u32x4*)(LO + (size_t)m * LORA_N + 2048 + c), g);
;         const float bs = COEF[(size_t)m * 16 + h];
.LBB0_315:
	s_andn2_b64 vcc, exec, s[0:1]
	s_cbranch_vccnz .LBB0_320
	s_cmp_eq_u32 s77, 5
	s_cbranch_scc0 .LBB0_320
	s_add_i32 s0, s92, 0
	s_waitcnt vmcnt(0)
	v_mov_b32_e32 v2, s0
	s_waitcnt lgkmcnt(0)
	ds_read_b64 v[0:1], v2 offset:112
	s_ashr_i32 s34, s10, 1
	s_cmpk_gt_i32 s34, 0x3fff
	s_waitcnt lgkmcnt(0)
	v_readfirstlane_b32 s0, v1
	v_readfirstlane_b32 s1, v0
	ds_read_b64 v[0:1], v2 offset:120
	s_waitcnt lgkmcnt(0)
	v_readfirstlane_b32 s2, v1
	v_readfirstlane_b32 s4, v0
	s_cbranch_scc1 .LBB0_320
	s_lshl_b32 s5, s52, 9
	s_and_b32 s5, s5, 0x200
	v_lshlrev_b32_e32 v16, 3, v185
	s_lshl_b32 s6, s96, 12
	v_or_b32_e32 v17, s5, v16
	s_add_u32 s4, s4, s6
	s_addc_u32 s5, s2, 0
	v_lshlrev_b32_e32 v96, 2, v17
	v_lshl_add_u64 v[4:5], s[4:5], 0, v[96:97]
	s_add_u32 s4, s1, s6
	s_addc_u32 s5, s0, 0
	v_lshl_add_u64 v[12:13], s[4:5], 0, v[96:97]
	global_load_dwordx4 v[0:3], v[4:5], off offset:16
	s_nop 0
	global_load_dwordx4 v[4:7], v[4:5], off
	s_nop 0
	global_load_dwordx4 v[8:11], v[12:13], off offset:16
	s_nop 0
	global_load_dwordx4 v[12:15], v[12:13], off
	v_and_b32_e32 v19, 64, v220
	v_xor_b32_e32 v18, 1, v220
	v_add_u32_e32 v19, 64, v19
	v_cmp_lt_i32_e32 vcc, v18, v19
	s_ashr_i32 s35, s34, 31
	s_lshl_b32 s0, s34, 6
	v_cndmask_b32_e32 v18, v220, v18, vcc
	v_lshlrev_b32_e32 v28, 2, v18
	v_xor_b32_e32 v18, 2, v220
	v_cmp_lt_i32_e32 vcc, v18, v19
	s_lshl_b64 s[4:5], s[34:35], 6
	s_add_u32 s4, s88, s4
	v_cndmask_b32_e32 v18, v220, v18, vcc
	v_lshlrev_b32_e32 v29, 2, v18
	v_xor_b32_e32 v18, 4, v220
	v_cmp_lt_i32_e32 vcc, v18, v19
	s_addc_u32 s5, s89, s5
	s_mul_i32 s2, s34, 0x1800
	v_cndmask_b32_e32 v18, v220, v18, vcc
	v_lshlrev_b32_e32 v30, 2, v18
	v_lshrrev_b32_e32 v18, 4, v17
	v_and_b32_e32 v96, 60, v18
	v_lshl_add_u64 v[18:19], s[4:5], 0, v[96:97]
	s_mov_b64 s[4:5], 0x31e00000
	v_lshl_add_u64 v[20:21], v[18:19], 0, s[4:5]
	s_mul_hi_i32 s1, s34, 0x1800
	s_add_u32 s4, s88, s2
	v_lshlrev_b32_e32 v96, 1, v17
	s_addc_u32 s5, s89, s1
	v_lshl_add_u64 v[18:19], s[4:5], 0, v[96:97]
	s_mov_b64 s[4:5], 0x20a01000
	v_lshl_add_u64 v[22:23], v[18:19], 0, s[4:5]
	s_lshl_b64 s[4:5], s[34:35], 12
	v_readlane_b32 s6, v254, 57
	v_readlane_b32 s7, v254, 58
	s_add_u32 s4, s6, s4
	s_addc_u32 s5, s7, s5
	v_lshl_add_u64 v[18:19], s[4:5], 0, v[96:97]
	s_mov_b64 s[4:5], 0x800
	v_and_b32_e32 v16, 56, v16
	v_lshl_add_u64 v[24:25], v[18:19], 0, s[4:5]
	v_readlane_b32 s4, v254, 3
	v_readlane_b32 s6, v254, 5
	v_readlane_b32 s8, v254, 7
	v_lshrrev_b32_e32 v27, 6, v17
	v_lshlrev_b32_e32 v96, 1, v16
	v_readlane_b32 s5, v254, 4
	v_readlane_b32 s7, v254, 6
	v_readlane_b32 s9, v254, 8
	v_mov_b64_e32 v[74:75], v[24:25]
	global_load_dwordx4 v[60:63], v[74:75], off
	global_load_dwordx4 v[64:67], v[22:23], off
	s_ashr_i32 s1, s34, 8
	v_and_or_b32 v76, s1, -16, v27
	v_ashrrev_i32_e32 v77, 31, v76
	s_and_b32 s2, s0, 0x3ffc0
	v_lshlrev_b64 v[76:77], 19, v[76:77]
	s_lshl_b32 s28, s2, 1
	v_lshl_add_u64 v[76:77], s[80:81], 0, v[76:77]
	v_lshl_add_u64 v[76:77], v[76:77], 0, s[28:29]
	v_lshl_add_u64 v[76:77], v[76:77], 0, v[96:97]
	global_load_dwordx4 v[68:71], v[76:77], off
	global_load_dword v72, v[20:21], off
	s_add_i32 s0, s0, s41
	v_lshl_add_u64 v[20:21], v[20:21], 0, s[6:7]
	v_lshl_add_u64 v[22:23], v[22:23], 0, s[4:5]
	v_lshl_add_u64 v[74:75], v[74:75], 0, s[8:9]
	s_add_i32 s34, s34, s93
	s_waitcnt vmcnt(0)
.LBB0_319:
	s_waitcnt vmcnt(1)
	v_mov_b32_e32 v32, v60
	v_mov_b32_e32 v33, v61
	v_mov_b32_e32 v34, v62
	v_mov_b32_e32 v35, v63
	v_mov_b32_e32 v36, v64
	v_mov_b32_e32 v37, v65
	v_mov_b32_e32 v38, v66
	v_mov_b32_e32 v39, v67
	v_mov_b32_e32 v16, v68
	v_mov_b32_e32 v17, v69
	v_mov_b32_e32 v18, v70
	v_mov_b32_e32 v19, v71
	v_mov_b32_e32 v26, v72
	s_cmpk_gt_i32 s34, 0x3fff
	s_cbranch_scc1 .Le6_nopf
	global_load_dwordx4 v[60:63], v[74:75], off
	global_load_dwordx4 v[64:67], v[22:23], off
	s_ashr_i32 s1, s34, 8
	v_and_or_b32 v76, s1, -16, v27
	v_ashrrev_i32_e32 v77, 31, v76
	s_and_b32 s2, s0, 0x3ffc0
	v_lshlrev_b64 v[76:77], 19, v[76:77]
	s_lshl_b32 s28, s2, 1
	v_lshl_add_u64 v[76:77], s[80:81], 0, v[76:77]
	v_lshl_add_u64 v[76:77], v[76:77], 0, s[28:29]
	v_lshl_add_u64 v[76:77], v[76:77], 0, v[96:97]
	global_load_dwordx4 v[68:71], v[76:77], off
	global_load_dword v72, v[20:21], off
	s_add_i32 s0, s0, s41
	v_lshl_add_u64 v[20:21], v[20:21], 0, s[6:7]
	v_lshl_add_u64 v[22:23], v[22:23], 0, s[4:5]
	v_lshl_add_u64 v[74:75], v[74:75], 0, s[8:9]
; __device__ __forceinline__ u32x4 pack8(const float (&f)[8]) { u32x4 w; w.x = pk_bf16(f[0], f[1]); w.y = pk_bf16(f[2], f[3]); w.z = pk_bf16(f[4], f[5]); w.w = pk_bf16(f[6], f[7]); return w; }
; __device__ __forceinline__ float sum8(float x) { x += __shfl_xor(x, 1); x += __shfl_xor(x, 2); x += __shfl_xor(x, 4); return x; }
; __device__ __forceinline__ void e6_phase(const bf16* LO, const float* COEF, const bf16* SV, const float* ln_w, const float* ln_b, bf16* mix, int gw, int ngw, int lane) {
;     ...
;         float s = 0.f;
; #pragma unroll
;         for (int e = 0; e < 8; ++e) s += y[e];
;         s = sum8(s);
;         const float mean = s * (1.0f / 64.0f); float q = 0.f;
; #pragma unroll
;         for (int e = 0; e < 8; ++e) { y[e] -= mean; q += y[e] * y[e]; }
;         q = sum8(q); const float rs = rsqrtf(q * (1.0f / 64.0f) + GN_EPS);
;         float o[8];
; #pragma unroll
;         for (int e = 0; e < 8; ++e) o[e] = (y[e] * rs * lw[e] + lb[e] + bs * v[e]) * g[e];
;         *(u32x4*)yp = pack8(o);
;     }
.Le6_nopf:
	s_add_i32 s34, s34, s93
	v_lshlrev_b32_e32 v44, 16, v32
	v_and_b32_e32 v45, 0xffff0000, v32
	v_add_f32_e32 v31, 0, v44
	v_lshlrev_b32_e32 v42, 16, v34
	v_and_b32_e32 v43, 0xffff0000, v34
	v_lshlrev_b32_e32 v34, 16, v33
	v_add_f32_e32 v31, v31, v45
	v_lshlrev_b32_e32 v40, 16, v35
	v_and_b32_e32 v41, 0xffff0000, v35
	v_and_b32_e32 v35, 0xffff0000, v33
	v_add_f32_e32 v31, v31, v34
	v_add_f32_e32 v31, v31, v35
	v_add_f32_e32 v31, v31, v42
	v_add_f32_e32 v31, v31, v43
	v_add_f32_e32 v31, v31, v40
	v_add_f32_e32 v31, v31, v41
	ds_bpermute_b32 v32, v28, v31
	s_waitcnt lgkmcnt(0)
	v_add_f32_e32 v31, v31, v32
	ds_bpermute_b32 v32, v29, v31
	s_waitcnt lgkmcnt(0)
	v_add_f32_e32 v31, v31, v32
	ds_bpermute_b32 v33, v30, v31
	v_lshlrev_b32_e32 v32, 16, v39
	s_waitcnt lgkmcnt(0)
	v_add_f32_e32 v31, v31, v33
	v_mul_f32_e32 v46, 0x3c800000, v31
	v_pk_add_f32 v[44:45], v[44:45], v[46:47] op_sel_hi:[1,0] neg_lo:[0,1] neg_hi:[0,1]
	v_pk_add_f32 v[34:35], v[34:35], v[46:47] op_sel_hi:[1,0] neg_lo:[0,1] neg_hi:[0,1]
	v_pk_add_f32 v[42:43], v[42:43], v[46:47] op_sel_hi:[1,0] neg_lo:[0,1] neg_hi:[0,1]
	v_pk_add_f32 v[40:41], v[40:41], v[46:47] op_sel_hi:[1,0] neg_lo:[0,1] neg_hi:[0,1]
	v_pk_mul_f32 v[46:47], v[44:45], v[44:45]
	v_pk_mul_f32 v[48:49], v[34:35], v[34:35]
	v_add_f32_e32 v31, v46, v47
	v_add_f32_e32 v31, v48, v31
	v_pk_mul_f32 v[50:51], v[42:43], v[42:43]
	v_add_f32_e32 v31, v49, v31
	v_add_f32_e32 v31, v50, v31
	v_pk_mul_f32 v[52:53], v[40:41], v[40:41]
	v_add_f32_e32 v31, v51, v31
	v_add_f32_e32 v31, v52, v31
	v_add_f32_e32 v31, v53, v31
	ds_bpermute_b32 v48, v28, v31
	v_and_b32_e32 v33, 0xffff0000, v39
	v_lshlrev_b32_e32 v46, 16, v38
	v_and_b32_e32 v47, 0xffff0000, v38
	v_lshlrev_b32_e32 v38, 16, v37
	s_waitcnt lgkmcnt(0)
	v_add_f32_e32 v31, v31, v48
	ds_bpermute_b32 v50, v29, v31
	v_and_b32_e32 v39, 0xffff0000, v37
	v_lshlrev_b32_e32 v48, 16, v36
	v_and_b32_e32 v49, 0xffff0000, v36
	v_lshlrev_b32_e32 v36, 16, v19
	s_waitcnt lgkmcnt(0)
	v_add_f32_e32 v31, v31, v50
	ds_bpermute_b32 v52, v30, v31
	v_and_b32_e32 v37, 0xffff0000, v19
	v_and_b32_e32 v53, 0xffff0000, v16
	v_lshlrev_b32_e32 v50, 16, v18
	v_and_b32_e32 v51, 0xffff0000, v18
	s_waitcnt lgkmcnt(0)
	v_add_f32_e32 v19, v31, v52
	v_mov_b32_e32 v31, 0x3a27c5ac
	v_fmamk_f32 v19, v19, 0x3c800000, v31
	v_mul_f32_e32 v31, 0x4b800000, v19
	v_cmp_gt_f32_e32 vcc, s12, v19
	v_lshlrev_b32_e32 v52, 16, v16
	v_lshlrev_b32_e32 v18, 16, v17
	v_cndmask_b32_e32 v19, v19, v31, vcc
	v_rsq_f32_e32 v31, v19
	v_and_b32_e32 v19, 0xffff0000, v17
	v_mul_f32_e32 v16, 0x45800000, v31
	v_cndmask_b32_e32 v16, v31, v16, vcc
	v_pk_mul_f32 v[44:45], v[44:45], v[16:17] op_sel_hi:[1,0]
	v_pk_mul_f32 v[34:35], v[34:35], v[16:17] op_sel_hi:[1,0]
	v_pk_mul_f32 v[42:43], v[42:43], v[16:17] op_sel_hi:[1,0]
	v_pk_mul_f32 v[16:17], v[40:41], v[16:17] op_sel_hi:[1,0]
	v_pk_fma_f32 v[40:41], v[12:13], v[44:45], v[4:5]
	v_pk_fma_f32 v[34:35], v[14:15], v[34:35], v[6:7]
	v_pk_fma_f32 v[42:43], v[8:9], v[42:43], v[0:1]
	v_pk_fma_f32 v[16:17], v[10:11], v[16:17], v[2:3]
	v_pk_fma_f32 v[40:41], v[26:27], v[52:53], v[40:41] op_sel_hi:[0,1,1]
	v_pk_fma_f32 v[18:19], v[26:27], v[18:19], v[34:35] op_sel_hi:[0,1,1]
	v_pk_fma_f32 v[34:35], v[26:27], v[50:51], v[42:43] op_sel_hi:[0,1,1]
	v_pk_fma_f32 v[16:17], v[26:27], v[36:37], v[16:17] op_sel_hi:[0,1,1]
	v_pk_mul_f32 v[36:37], v[40:41], v[48:49]
	v_pk_mul_f32 v[18:19], v[18:19], v[38:39]
	v_pk_mul_f32 v[34:35], v[34:35], v[46:47]
	v_pk_mul_f32 v[32:33], v[16:17], v[32:33]
	v_cvt_pk_bf16_f32 v16, v36, v37
	v_cvt_pk_bf16_f32 v17, v18, v19
	v_cvt_pk_bf16_f32 v18, v34, v35
	v_cvt_pk_bf16_f32 v19, v32, v33
	global_store_dwordx4 v[24:25], v[16:19], off
	v_lshl_add_u64 v[24:25], v[24:25], 0, s[8:9]
	s_sub_i32 s1, s34, s93
	s_cmpk_gt_i32 s1, 0x3fff
	s_cbranch_scc0 .LBB0_319
